# v45 plus leaders bump the per-XCC generation word before their own acquire invalidate instead of after
# baseline (speedup 1.0000x reference)
.LBB0_128:
	s_or_b64 exec, exec, s[20:21]
	s_mov_b64 s[4:5], exec
	v_mbcnt_lo_u32_b32 v1, s4, 0
	v_mbcnt_hi_u32_b32 v1, s5, v1
	v_cmp_eq_u32_e32 vcc, 0, v1
	s_waitcnt vmcnt(0)
	s_and_saveexec_b64 s[20:21], vcc
	s_cbranch_execz .LBB0_130
	s_bcnt1_i32_b64 s0, s[4:5]
	v_mov_b32_e32 v1, 0x2000
	v_mov_b32_e32 v2, s0
	global_atomic_add v1, v2, s[8:9] offset:1024
.LBB0_130:
	s_or_b64 exec, exec, s[20:21]
	buffer_inv sc1
	s_waitcnt vmcnt(0)

.LBB0_269:
	s_or_b64 exec, exec, s[12:13]
	s_mov_b64 s[4:5], exec
	v_mbcnt_lo_u32_b32 v1, s4, 0
	v_mbcnt_hi_u32_b32 v1, s5, v1
	v_cmp_eq_u32_e32 vcc, 0, v1
	s_waitcnt vmcnt(0)
	s_and_saveexec_b64 s[12:13], vcc
	s_cbranch_execz .LBB0_271
	s_bcnt1_i32_b64 s0, s[4:5]
	v_mov_b32_e32 v1, 0x2000
	v_mov_b32_e32 v2, s0
	global_atomic_add v1, v2, s[8:9] offset:1024
.LBB0_271:
	s_or_b64 exec, exec, s[12:13]
	buffer_inv sc1
	s_waitcnt vmcnt(0)

.LBB0_357:
	s_or_b64 exec, exec, s[14:15]
	s_mov_b64 s[4:5], exec
	v_mbcnt_lo_u32_b32 v1, s4, 0
	v_mbcnt_hi_u32_b32 v1, s5, v1
	v_cmp_eq_u32_e32 vcc, 0, v1
	s_waitcnt vmcnt(0)
	s_and_saveexec_b64 s[14:15], vcc
	s_cbranch_execz .LBB0_359
	s_bcnt1_i32_b64 s0, s[4:5]
	v_mov_b32_e32 v1, 0x2000
	v_mov_b32_e32 v2, s0
	global_atomic_add v1, v2, s[8:9] offset:1024
.LBB0_359:
	s_or_b64 exec, exec, s[14:15]
	buffer_inv sc1
	s_waitcnt vmcnt(0)

.LBB0_439:
	s_or_b64 exec, exec, s[10:11]
	s_mov_b64 s[4:5], exec
	v_mbcnt_lo_u32_b32 v1, s4, 0
	v_mbcnt_hi_u32_b32 v1, s5, v1
	v_cmp_eq_u32_e32 vcc, 0, v1
	s_waitcnt vmcnt(0)
	s_and_saveexec_b64 s[10:11], vcc
	s_cbranch_execz .LBB0_441
	s_bcnt1_i32_b64 s0, s[4:5]
	v_mov_b32_e32 v1, 0x2000
	v_mov_b32_e32 v2, s0
	global_atomic_add v1, v2, s[8:9] offset:1024
.LBB0_441:
	s_or_b64 exec, exec, s[10:11]
	buffer_inv sc1
	s_waitcnt vmcnt(0)

.LBB0_569:
	s_or_b64 exec, exec, s[16:17]
	s_mov_b64 s[4:5], exec
	v_mbcnt_lo_u32_b32 v1, s4, 0
	v_mbcnt_hi_u32_b32 v1, s5, v1
	v_cmp_eq_u32_e32 vcc, 0, v1
	s_waitcnt vmcnt(0)
	s_and_saveexec_b64 s[16:17], vcc
	s_cbranch_execz .LBB0_571
	s_bcnt1_i32_b64 s0, s[4:5]
	v_mov_b32_e32 v1, 0x2000
	v_mov_b32_e32 v2, s0
	global_atomic_add v1, v2, s[14:15] offset:1024
.LBB0_571:
	s_or_b64 exec, exec, s[16:17]
	buffer_inv sc1
	s_waitcnt vmcnt(0)

.LBB0_637:
	s_or_b64 exec, exec, s[10:11]
	s_mov_b64 s[4:5], exec
	v_mbcnt_lo_u32_b32 v1, s4, 0
	v_mbcnt_hi_u32_b32 v1, s5, v1
	v_cmp_eq_u32_e32 vcc, 0, v1
	s_waitcnt vmcnt(0)
	s_and_saveexec_b64 s[10:11], vcc
	s_cbranch_execz .LBB0_639
	s_bcnt1_i32_b64 s3, s[4:5]
	v_mov_b32_e32 v1, 0x2000
	v_mov_b32_e32 v2, s3
	global_atomic_add v1, v2, s[0:1] offset:1024
